# chunk-SGU item loop re-pipelined (A/bias loads ahead of the next-item prefetch, stats prefetched, batched LDS epilogue) + ctx GEMM operands pulled into cache at the end of the in-proj phase
# speedup vs baseline: 1.0137x; 1.0008x over previous
; #define PG8_WAIT_V(n) asm volatile("s_waitcnt vmcnt(" #n ")" ::: "memory")
; #define PG8_BAR __builtin_amdgcn_s_barrier()
; template <class Epi, class Sched>
; __device__ __forceinline__ void gemm_phase(LAS unsigned char* lds, const Gemm g, const Sched& S, const Epi& E) {
;     ...
;     PG8_WAIT_V(0);
;     if (wr == 0) PG8_BAR;
;     PG8_BAR;
.LBB0_169:
	s_lshl_b32 s98, s24, 9
	v_add_u32_e32 v240, s98, v167
	v_lshlrev_b32_e32 v241, 5, v240
	v_lshlrev_b32_e32 v242, 4, v240
	s_add_u32 s98, s22, 0x3400000
	s_addc_u32 s99, s23, 0
	s_add_u32 s100, s22, 0x200000
	s_addc_u32 s101, s23, 0
	global_load_dwordx4 v[244:247], v241, s[98:99]
	global_load_dwordx4 v[248:251], v241, s[98:99] offset:16
	global_load_dwordx4 v[236:239], v242, s[100:101]
	s_waitcnt vmcnt(0)
	s_cmpk_gt_u32 s94, 0xff
	s_cbranch_scc1 .LBB0_130
	s_barrier
	s_branch .LBB0_130

; #define LAS __attribute__((address_space(3)))
; __device__ __forceinline__ int opaque_tid() { int t = threadIdx.x; asm volatile("" : "+v"(t)); return t; }
; __device__ __forceinline__ void sgu_list(LAS unsigned char* lds, const Params& P, int i0, int istride) {
;     const int tid = opaque_tid(), lane = tid & 63, wid = __builtin_amdgcn_readfirstlane(tid >> 6);
;     if (i0 >= 1024) return;
;     LAS unsigned char* VT = lds;
;     LAS unsigned char* UG = lds + 128 * VT_PITCH;
;     LAS float* ST = (LAS float*)(lds + 2 * 128 * VT_PITCH);
;     bf16_t* Z = (bf16_t*)(P.ws + WS_Z); const bf16_t* SguW = (const bf16_t*)(P.ws + WS_SGUW);
;     SguRegs R;
;     sgu_load(R, P, Z, (size_t)(i0 >> 7) * SEQ + ((i0 >> 3) & 15) * 128, i0 & 7, tid);
;     const int cp = tid & 63, tg = tid >> 6, c0 = 2 * cp;
;     const int rr = tid >> 4, cc = (tid & 15) * 8;
;     const int pb = wid & 3, cb0 = (wid >> 2) * 2, ml = lane & 31, kh = lane >> 5;
;     for (int i = i0; i < 1024; i += istride) {
;         const int gg = i & 7; const size_t R0 = (size_t)(i >> 7) * SEQ + ((i >> 3) & 15) * 128;
;         if (tid < 128) { const f32x4* sp = (const f32x4*)((const float*)(P.ws + WS_STATS) + (R0 + tid) * 32); float s1 = 0.f, ss = 0.f;
.LBB0_226:
	v_readlane_b32 s4, v255, 0
	s_cmp_lt_i32 s4, 4
	s_cselect_b64 s[2:3], -1, 0
	s_and_b64 s[10:11], s[2:3], s[0:1]
	s_andn2_b64 vcc, exec, s[10:11]
	v_readlane_b32 s5, v255, 1
	v_readlane_b32 s6, v255, 2
	v_readlane_b32 s7, v255, 3
	s_cbranch_vccnz .LBB0_318
	s_min_i32 s2, s34, 32
	v_writelane_b32 v255, s10, 16
	s_cmp_ge_i32 s24, s2
	s_mov_b64 s[0:1], -1
	v_writelane_b32 v255, s11, 17
	s_cbranch_scc0 .LBB0_237
	v_mov_b32_e32 v44, v167
	s_sub_i32 s0, s24, s2
	s_cmpk_gt_i32 s0, 0x3ff
	v_ashrrev_i32_e32 v0, 6, v44
	s_nop 0
	v_readfirstlane_b32 s4, v0
	s_cbranch_scc1 .LBB0_236
	s_sub_i32 s3, s34, s2
	s_add_u32 s10, s22, 0x5400000
	s_addc_u32 s11, s23, 0
	s_ashr_i32 s6, s0, 7
	s_ashr_i32 s7, s6, 31
	s_lshl_b32 s1, s0, 4
	s_and_b32 s14, s0, 7
	s_lshl_b64 s[6:7], s[6:7], 11
	s_and_b32 s1, s1, 0x780
	s_lshl_b32 s15, s14, 14
	s_or_b32 s5, s6, s1
	v_cmp_gt_u32_e32 vcc, 0x80, v44
	s_nop 1
	v_cndmask_b32_e32 v216, 0, v44, vcc
	v_mov_b32_e32 v217, 0
	s_mov_b32 s98, s5
	s_mov_b32 s99, s7
	v_lshl_add_u64 v[218:219], s[98:99], 0, v[216:217]
	v_lshlrev_b64 v[218:219], 7, v[218:219]
	s_add_u32 s98, s22, 0xf800000
	s_addc_u32 s99, s23, 0
	v_lshl_add_u64 v[218:219], s[98:99], 0, v[218:219]
	global_load_dwordx4 v[168:171], v[218:219], off
	global_load_dwordx4 v[172:175], v[218:219], off offset:16
	global_load_dwordx4 v[176:179], v[218:219], off offset:32
	global_load_dwordx4 v[180:183], v[218:219], off offset:48
	global_load_dwordx4 v[184:187], v[218:219], off offset:64
	global_load_dwordx4 v[188:191], v[218:219], off offset:80
	global_load_dwordx4 v[192:195], v[218:219], off offset:96
	global_load_dwordx4 v[196:199], v[218:219], off offset:112
	s_or_b32 s0, s15, 0x60000
	v_ashrrev_i32_e32 v2, 3, v44
	v_lshlrev_b32_e32 v1, 1, v44
	v_and_b32_e32 v46, -8, v2
	s_add_u32 s0, s5, s0
	v_and_b32_e32 v1, 0x7e, v1
	v_ashrrev_i32_e32 v47, 31, v46
	s_addc_u32 s1, s7, 0
	v_lshl_add_u64 v[2:3], s[0:1], 0, v[46:47]
	v_lshlrev_b32_e32 v48, 1, v1
	v_mov_b32_e32 v49, 0
	v_lshl_add_u64 v[50:51], s[10:11], 0, v[48:49]
	v_lshlrev_b64 v[2:3], 8, v[2:3]
	v_lshl_add_u64 v[2:3], v[50:51], 0, v[2:3]
	s_movk_i32 s6, 0x4000
	s_bitset1_b32 s15, 18
	global_load_dword v62, v[2:3], off
	global_load_dword v63, v[2:3], off offset:256
	global_load_dword v64, v[2:3], off offset:512
	global_load_dword v65, v[2:3], off offset:768
	global_load_dword v66, v[2:3], off offset:1024
	global_load_dword v67, v[2:3], off offset:1280
	global_load_dword v68, v[2:3], off offset:1536
	global_load_dword v69, v[2:3], off offset:1792
	v_add_co_u32_e32 v2, vcc, s6, v2
	v_ashrrev_i32_e32 v52, 4, v44
	s_add_u32 s0, s5, s15
	v_addc_co_u32_e32 v3, vcc, 0, v3, vcc
	v_ashrrev_i32_e32 v53, 31, v52
	s_addc_u32 s1, s7, 0
	v_lshlrev_b32_e32 v4, 4, v44
	global_load_dword v70, v[2:3], off
	global_load_dword v71, v[2:3], off offset:256
	global_load_dword v72, v[2:3], off offset:512
	global_load_dword v73, v[2:3], off offset:768
	global_load_dword v74, v[2:3], off offset:1024
	global_load_dword v75, v[2:3], off offset:1280
	global_load_dword v76, v[2:3], off offset:1536
	global_load_dword v77, v[2:3], off offset:1792
	v_lshl_add_u64 v[2:3], s[0:1], 0, v[52:53]
	v_and_b32_e32 v48, 0xf0, v4
	v_lshl_add_u64 v[54:55], s[10:11], 0, v[48:49]
	v_lshlrev_b64 v[2:3], 8, v[2:3]
	v_lshl_add_u64 v[2:3], v[54:55], 0, v[2:3]
	s_movk_i32 s0, 0x2000
	v_add_co_u32_e32 v4, vcc, s0, v2
	s_movk_i32 s0, 0x6000
	s_nop 0
	v_addc_co_u32_e32 v5, vcc, 0, v3, vcc
	global_load_dwordx4 v[16:19], v[2:3], off
	global_load_dwordx4 v[20:23], v[4:5], off
	v_add_co_u32_e32 v4, vcc, s6, v2
	v_lshlrev_b32_e32 v78, 2, v1
	s_nop 0
	v_addc_co_u32_e32 v5, vcc, 0, v3, vcc
	v_add_co_u32_e32 v2, vcc, s0, v2
	v_lshl_or_b32 v1, s14, 9, v78
	s_nop 0
	v_addc_co_u32_e32 v3, vcc, 0, v3, vcc
	global_load_dwordx4 v[24:27], v[4:5], off
	global_load_dwordx4 v[28:31], v[2:3], off
	s_waitcnt lgkmcnt(0)
	global_load_dwordx2 v[58:59], v1, s[66:67]
	global_load_dwordx2 v[60:61], v1, s[8:9]
	v_and_b32_e32 v1, 63, v44
	v_bfe_u32 v5, v44, 5, 1
	s_movk_i32 s7, 0x220
	v_mad_u32_u24 v1, v1, s7, 0
	v_add_u32_e32 v6, 0, v48
	s_lshl_b32 s7, s4, 5
	v_lshlrev_b32_e32 v48, 4, v5
	s_lshl_b32 s4, s4, 4
	v_and_b32_e32 v4, 31, v44
	s_and_b32 s7, s7, 0x60
	v_lshl_add_u64 v[2:3], s[22:23], 0, v[48:49]
	s_mov_b64 s[10:11], 0x1100000
	s_andn2_b32 s4, s4, 63
	v_lshl_add_u64 v[56:57], v[2:3], 0, s[10:11]
	s_movk_i32 s10, 0x110
	v_or_b32_e32 v81, s7, v4
	v_or_b32_e32 v4, s4, v4
	s_add_i32 s5, 0, 0x11000
	v_mul_lo_u32 v10, v4, s10
	v_lshl_add_u32 v11, v4, 1, 0
	v_or_b32_e32 v4, 32, v4
	v_mul_lo_u32 v3, v52, s10
	v_mul_lo_u32 v12, v4, s10
	s_add_u32 s10, s22, 0xf800000
	s_addc_u32 s11, s23, 0
	s_lshl_b32 s4, s2, 1
	v_lshl_or_b32 v80, v5, 2, s7
	v_lshlrev_b32_e32 v7, 4, v0
	v_lshl_add_u32 v0, v0, 3, 64
	s_sub_i32 s7, s34, s4
	s_lshl_b32 s4, s34, 4
	s_lshl_b32 s14, s2, 5
	s_movk_i32 s0, 0x80
	v_add_u32_e32 v2, 0, v48
	v_and_b32_e32 v5, 0xffffffc0, v44
	v_lshlrev_b32_e32 v8, 3, v0
	v_lshlrev_b32_e32 v0, 1, v0
	v_mul_u32_u24_e32 v9, 0x110, v80
	v_lshl_add_u32 v4, v4, 1, 0
	s_sub_i32 s18, s4, s14
	s_lshl_b32 s14, s2, 4
	v_cmp_gt_i32_e64 s[0:1], s0, v44
	v_ashrrev_i32_e32 v45, 31, v44
	v_lshl_add_u32 v79, v44, 3, s5
	s_lshl_b32 s19, s24, 4
	s_sub_i32 s20, s4, s14
	s_sub_i32 s21, 0, s14
	s_sub_i32 s25, 0, s2
	s_mov_b32 s26, 0x3a800000
	s_mov_b32 s27, 0xf800000
	v_mov_b32_e32 v82, 0x260
	v_add_u32_e32 v83, v1, v7
	v_add_u32_e32 v84, v1, v0
	v_add_u32_e32 v85, v2, v10
	v_add_u32_e32 v86, v11, v9
	v_add_u32_e32 v87, v2, v12
	v_add_u32_e32 v88, v4, v9
	v_add_u32_e32 v89, s5, v5
	v_add_u32_e32 v90, s5, v8
	v_add_u32_e32 v91, v6, v3
	s_mov_b32 s28, s24
	s_waitcnt vmcnt(0)
	s_branch .LBB0_231
; #define LAS __attribute__((address_space(3)))
; __device__ __forceinline__ float bf2f(bf16_t h) { return __uint_as_float(((unsigned)h) << 16); }
; __device__ __forceinline__ bf16_t f2bf(float f) { return (bf16_t)(cvt_pk_bf16(f, 0.f) & 0xffffu); }
; __device__ __forceinline__ void sgu_list(LAS unsigned char* lds, const Params& P, int i0, int istride) {
;     ...
;         bf16x8 Aw[8];
;         { const bf16_t* ap = SguW + ((size_t)gg * 128 + pb * 32 + ml) * 128 + 8 * kh;
; #pragma unroll
;           for (int ks = 0; ks < 8; ++ks) Aw[ks] = *(const bf16x8*)(ap + 16 * ks); }
;         float bsv[16];
; #pragma unroll
;         for (int v = 0; v < 16; ++v) bsv[v] = P.sgu_b[gg * 128 + pb * 32 + (v & 3) + 8 * (v >> 2) + 4 * kh];
; #pragma unroll
;         for (int cbi = 0; cbi < 2; ++cbi) { const int ccol = (cb0 + cbi) * 32 + ml;
;             f32x16 acc;
; #pragma unroll
;             for (int v = 0; v < 16; ++v) acc[v] = 0.f;
;             const LAS unsigned char* bp = VT + ccol * VT_PITCH + 16 * kh;
; #pragma unroll
;             for (int ks = 0; ks < 8; ++ks) { const bf16x8 Bf = *(const LAS bf16x8*)(bp + 32 * ks); acc = __builtin_amdgcn_mfma_f32_32x32x16_bf16(Aw[ks], Bf, acc, 0, 0, 0); }
; #pragma unroll
;             for (int v = 0; v < 16; ++v) { const int p = pb * 32 + (v & 3) + 8 * (v >> 2) + 4 * kh;
;                 LAS bf16_t* up = (LAS bf16_t*)(UG + p * VT_PITCH + ccol * 2);
;                 *up = f2bf(bf2f(*up) * (acc[v] + bsv[v])); } }
.LBB0_230:
	s_and_b32 s4, s29, 7
	s_lshl_b32 s4, s4, 14
	s_bitset1_b32 s4, 18
	s_add_u32 s4, s4, s14
	s_addc_u32 s5, 0, s15
	s_add_i32 s28, s28, s3
	s_add_i32 s19, s19, s20
	s_waitcnt lgkmcnt(0)
	s_barrier
	ds_read_b128 v[124:127], v85
	ds_read_b128 v[128:131], v85 offset:32
	ds_read_b128 v[32:35], v85 offset:64
	ds_read_b128 v[36:39], v85 offset:96
	ds_read_b128 v[40:43], v85 offset:128
	ds_read_b128 v[156:159], v85 offset:160
	ds_read_b128 v[160:163], v85 offset:192
	ds_read_b128 v[222:225], v85 offset:224
	s_waitcnt vmcnt(41) lgkmcnt(7)
	v_mfma_f32_32x32x16_bf16 v[0:15], v[92:95], v[124:127], 0
	s_waitcnt vmcnt(40) lgkmcnt(6)
	v_mfma_f32_32x32x16_bf16 v[0:15], v[96:99], v[128:131], v[0:15]
	s_waitcnt vmcnt(39) lgkmcnt(5)
	v_mfma_f32_32x32x16_bf16 v[0:15], v[100:103], v[32:35], v[0:15]
	s_waitcnt vmcnt(38) lgkmcnt(4)
	v_mfma_f32_32x32x16_bf16 v[0:15], v[104:107], v[36:39], v[0:15]
	s_waitcnt vmcnt(37) lgkmcnt(3)
	v_mfma_f32_32x32x16_bf16 v[0:15], v[108:111], v[40:43], v[0:15]
	s_waitcnt vmcnt(36) lgkmcnt(2)
	v_mfma_f32_32x32x16_bf16 v[0:15], v[112:115], v[156:159], v[0:15]
	s_waitcnt vmcnt(35) lgkmcnt(1)
	v_mfma_f32_32x32x16_bf16 v[0:15], v[116:119], v[160:163], v[0:15]
	s_waitcnt vmcnt(34) lgkmcnt(0)
	v_mfma_f32_32x32x16_bf16 v[0:15], v[120:123], v[222:225], v[0:15]
	ds_read_b128 v[124:127], v87
	ds_read_b128 v[128:131], v87 offset:32
	ds_read_b128 v[32:35], v87 offset:64
	ds_read_b128 v[36:39], v87 offset:96
	ds_read_b128 v[40:43], v87 offset:128
	ds_read_b128 v[156:159], v87 offset:160
	ds_read_b128 v[160:163], v87 offset:192
	ds_read_b128 v[222:225], v87 offset:224
	ds_read_u16 v200, v86 offset:34816
	ds_read_u16 v201, v86 offset:35088
	ds_read_u16 v202, v86 offset:35360
	ds_read_u16 v203, v86 offset:35632
	ds_read_u16 v204, v86 offset:36992
	ds_read_u16 v205, v86 offset:37264
	ds_read_u16 v206, v86 offset:37536
	ds_read_u16 v207, v86 offset:37808
	ds_read_u16 v208, v86 offset:39168
	ds_read_u16 v209, v86 offset:39440
	ds_read_u16 v210, v86 offset:39712
	ds_read_u16 v211, v86 offset:39984
	ds_read_u16 v212, v86 offset:41344
	ds_read_u16 v213, v86 offset:41616
	ds_read_u16 v214, v86 offset:41888
	ds_read_u16 v215, v86 offset:42160
	s_waitcnt lgkmcnt(15)
	v_mfma_f32_32x32x16_bf16 v[226:241], v[92:95], v[124:127], 0
	v_mfma_f32_32x32x16_bf16 v[226:241], v[96:99], v[128:131], v[226:241]
	v_mfma_f32_32x32x16_bf16 v[226:241], v[100:103], v[32:35], v[226:241]
	v_mfma_f32_32x32x16_bf16 v[226:241], v[104:107], v[36:39], v[226:241]
	v_mfma_f32_32x32x16_bf16 v[226:241], v[108:111], v[40:43], v[226:241]
	v_mfma_f32_32x32x16_bf16 v[226:241], v[112:115], v[156:159], v[226:241]
	v_mfma_f32_32x32x16_bf16 v[226:241], v[116:119], v[160:163], v[226:241]
	v_mfma_f32_32x32x16_bf16 v[226:241], v[120:123], v[222:225], v[226:241]
	s_waitcnt lgkmcnt(0)
	ds_read_u16 v133, v88 offset:34816
	ds_read_u16 v134, v88 offset:35088
	ds_read_u16 v135, v88 offset:35360
	ds_read_u16 v136, v88 offset:35632
	ds_read_u16 v137, v88 offset:36992
	ds_read_u16 v138, v88 offset:37264
	ds_read_u16 v139, v88 offset:37536
	ds_read_u16 v242, v88 offset:37808
	ds_read_u16 v243, v88 offset:39168
	ds_read_u16 v244, v88 offset:39440
	ds_read_u16 v245, v88 offset:39712
	ds_read_u16 v246, v88 offset:39984
	ds_read_u16 v247, v88 offset:41344
	ds_read_u16 v248, v88 offset:41616
	ds_read_u16 v249, v88 offset:41888
	ds_read_u16 v250, v88 offset:42160
	s_waitcnt vmcnt(33)
	v_add_f32_e32 v0, v140, v0
	v_lshlrev_b32_e32 v200, 16, v200
	v_mul_f32_e32 v200, v0, v200
	v_add_f32_e32 v1, v141, v1
	v_lshlrev_b32_e32 v201, 16, v201
	v_mul_f32_e32 v201, v1, v201
	v_add_f32_e32 v2, v142, v2
	v_lshlrev_b32_e32 v202, 16, v202
	v_mul_f32_e32 v202, v2, v202
	v_add_f32_e32 v3, v143, v3
	v_lshlrev_b32_e32 v203, 16, v203
	v_mul_f32_e32 v203, v3, v203
	s_waitcnt vmcnt(32)
	v_add_f32_e32 v4, v144, v4
	v_lshlrev_b32_e32 v204, 16, v204
	v_mul_f32_e32 v204, v4, v204
	v_add_f32_e32 v5, v145, v5
	v_lshlrev_b32_e32 v205, 16, v205
	v_mul_f32_e32 v205, v5, v205
	v_add_f32_e32 v6, v146, v6
	v_lshlrev_b32_e32 v206, 16, v206
	v_mul_f32_e32 v206, v6, v206
	v_add_f32_e32 v7, v147, v7
	v_lshlrev_b32_e32 v207, 16, v207
	v_mul_f32_e32 v207, v7, v207
	s_waitcnt vmcnt(31)
	v_add_f32_e32 v8, v148, v8
	v_lshlrev_b32_e32 v208, 16, v208
	v_mul_f32_e32 v208, v8, v208
	v_add_f32_e32 v9, v149, v9
	v_lshlrev_b32_e32 v209, 16, v209
	v_mul_f32_e32 v209, v9, v209
	v_add_f32_e32 v10, v150, v10
	v_lshlrev_b32_e32 v210, 16, v210
	v_mul_f32_e32 v210, v10, v210
	v_add_f32_e32 v11, v151, v11
	v_lshlrev_b32_e32 v211, 16, v211
	v_mul_f32_e32 v211, v11, v211
	s_waitcnt vmcnt(30)
	v_add_f32_e32 v12, v152, v12
	v_lshlrev_b32_e32 v212, 16, v212
	v_mul_f32_e32 v212, v12, v212
	v_add_f32_e32 v13, v153, v13
	v_lshlrev_b32_e32 v213, 16, v213
	v_mul_f32_e32 v213, v13, v213
	v_add_f32_e32 v14, v154, v14
	v_lshlrev_b32_e32 v214, 16, v214
	v_mul_f32_e32 v214, v14, v214
	v_add_f32_e32 v15, v155, v15
	v_lshlrev_b32_e32 v215, 16, v215
	v_mul_f32_e32 v215, v15, v215
	v_cvt_pk_bf16_f32 v200, v200, v49
	v_cvt_pk_bf16_f32 v201, v201, v49
	v_cvt_pk_bf16_f32 v202, v202, v49
	v_cvt_pk_bf16_f32 v203, v203, v49
	v_cvt_pk_bf16_f32 v204, v204, v49
	v_cvt_pk_bf16_f32 v205, v205, v49
	v_cvt_pk_bf16_f32 v206, v206, v49
	v_cvt_pk_bf16_f32 v207, v207, v49
	v_cvt_pk_bf16_f32 v208, v208, v49
	v_cvt_pk_bf16_f32 v209, v209, v49
	v_cvt_pk_bf16_f32 v210, v210, v49
	v_cvt_pk_bf16_f32 v211, v211, v49
	v_cvt_pk_bf16_f32 v212, v212, v49
	v_cvt_pk_bf16_f32 v213, v213, v49
	v_cvt_pk_bf16_f32 v214, v214, v49
	v_cvt_pk_bf16_f32 v215, v215, v49
	s_nop 0
	ds_write_b16 v86, v200 offset:34816
	ds_write_b16 v86, v201 offset:35088
	ds_write_b16 v86, v202 offset:35360
	ds_write_b16 v86, v203 offset:35632
	ds_write_b16 v86, v204 offset:36992
	ds_write_b16 v86, v205 offset:37264
	ds_write_b16 v86, v206 offset:37536
	ds_write_b16 v86, v207 offset:37808
	ds_write_b16 v86, v208 offset:39168
	ds_write_b16 v86, v209 offset:39440
	ds_write_b16 v86, v210 offset:39712
	ds_write_b16 v86, v211 offset:39984
	ds_write_b16 v86, v212 offset:41344
	ds_write_b16 v86, v213 offset:41616
	ds_write_b16 v86, v214 offset:41888
	ds_write_b16 v86, v215 offset:42160
	s_waitcnt lgkmcnt(15)
; #define LAS __attribute__((address_space(3)))
; __device__ __forceinline__ float bf2f(bf16_t h) { return __uint_as_float(((unsigned)h) << 16); }
; __device__ __forceinline__ bf16_t f2bf(float f) { return (bf16_t)(cvt_pk_bf16(f, 0.f) & 0xffffu); }
; #define LDS_BARRIER() do { asm volatile("s_waitcnt lgkmcnt(0)" ::: "memory"); __builtin_amdgcn_s_barrier(); asm volatile("" ::: "memory"); } while (0)
; __device__ __forceinline__ void sgu_list(LAS unsigned char* lds, const Params& P, int i0, int istride) {
;     ...
;     for (int i = i0; i < 1024; i += istride) {
;         const int gg = i & 7; const size_t R0 = (size_t)(i >> 7) * SEQ + ((i >> 3) & 15) * 128;
;         if (tid < 128) { const f32x4* sp = (const f32x4*)((const float*)(P.ws + WS_STATS) + (R0 + tid) * 32); float s1 = 0.f, ss = 0.f;
; #pragma unroll
;             for (int k = 0; k < 8; ++k) { const f32x4 v = sp[k]; s1 += v[0] + v[2]; ss += v[1] + v[3]; }
;             const float mean = s1 * (1.0f / 1024.0f), var = fmaxf(ss * (1.0f / 1024.0f) - mean * mean, 0.f);
;             ST[tid * 2] = mean; ST[tid * 2 + 1] = 1.0f / sqrtf(var + 1e-5f); }
;     ...
;             for (int v = 0; v < 16; ++v) { const int p = pb * 32 + (v & 3) + 8 * (v >> 2) + 4 * kh;
;                 LAS bf16_t* up = (LAS bf16_t*)(UG + p * VT_PITCH + ccol * 2);
;                 *up = f2bf(bf2f(*up) * (acc[v] + bsv[v])); } }
;         LDS_BARRIER();
; #pragma unroll
;         for (int k = 0; k < 4; ++k) *(u32x4*)(Z + ZSLAB(16 + gg, R0 + rr + 32 * k) + cc) = *(const LAS u32x4*)(UG + (rr + 32 * k) * VT_PITCH + cc * 2);
	v_add_f32_e32 v226, v140, v226
	v_lshlrev_b32_e32 v133, 16, v133
	v_mul_f32_e32 v133, v226, v133
	v_add_f32_e32 v227, v141, v227
	v_lshlrev_b32_e32 v134, 16, v134
	v_mul_f32_e32 v134, v227, v134
	v_add_f32_e32 v228, v142, v228
	v_lshlrev_b32_e32 v135, 16, v135
	v_mul_f32_e32 v135, v228, v135
	v_add_f32_e32 v229, v143, v229
	v_lshlrev_b32_e32 v136, 16, v136
	v_mul_f32_e32 v136, v229, v136
	v_add_f32_e32 v230, v144, v230
	v_lshlrev_b32_e32 v137, 16, v137
	v_mul_f32_e32 v137, v230, v137
	v_add_f32_e32 v231, v145, v231
	v_lshlrev_b32_e32 v138, 16, v138
	v_mul_f32_e32 v138, v231, v138
	v_add_f32_e32 v232, v146, v232
	v_lshlrev_b32_e32 v139, 16, v139
	v_mul_f32_e32 v139, v232, v139
	v_add_f32_e32 v233, v147, v233
	v_lshlrev_b32_e32 v242, 16, v242
	v_mul_f32_e32 v242, v233, v242
	v_add_f32_e32 v234, v148, v234
	v_lshlrev_b32_e32 v243, 16, v243
	v_mul_f32_e32 v243, v234, v243
	v_add_f32_e32 v235, v149, v235
	v_lshlrev_b32_e32 v244, 16, v244
	v_mul_f32_e32 v244, v235, v244
	v_add_f32_e32 v236, v150, v236
	v_lshlrev_b32_e32 v245, 16, v245
	v_mul_f32_e32 v245, v236, v245
	v_add_f32_e32 v237, v151, v237
	v_lshlrev_b32_e32 v246, 16, v246
	v_mul_f32_e32 v246, v237, v246
	v_add_f32_e32 v238, v152, v238
	v_lshlrev_b32_e32 v247, 16, v247
	v_mul_f32_e32 v247, v238, v247
	v_add_f32_e32 v239, v153, v239
	v_lshlrev_b32_e32 v248, 16, v248
	v_mul_f32_e32 v248, v239, v248
	v_add_f32_e32 v240, v154, v240
	v_lshlrev_b32_e32 v249, 16, v249
	v_mul_f32_e32 v249, v240, v249
	v_add_f32_e32 v241, v155, v241
	v_lshlrev_b32_e32 v250, 16, v250
	v_mul_f32_e32 v250, v241, v250
	v_cvt_pk_bf16_f32 v133, v133, v49
	v_cvt_pk_bf16_f32 v134, v134, v49
	v_cvt_pk_bf16_f32 v135, v135, v49
	v_cvt_pk_bf16_f32 v136, v136, v49
	v_cvt_pk_bf16_f32 v137, v137, v49
	v_cvt_pk_bf16_f32 v138, v138, v49
	v_cvt_pk_bf16_f32 v139, v139, v49
	v_cvt_pk_bf16_f32 v242, v242, v49
	v_cvt_pk_bf16_f32 v243, v243, v49
	v_cvt_pk_bf16_f32 v244, v244, v49
	v_cvt_pk_bf16_f32 v245, v245, v49
	v_cvt_pk_bf16_f32 v246, v246, v49
	v_cvt_pk_bf16_f32 v247, v247, v49
	v_cvt_pk_bf16_f32 v248, v248, v49
	v_cvt_pk_bf16_f32 v249, v249, v49
	v_cvt_pk_bf16_f32 v250, v250, v49
	s_nop 0
	ds_write_b16 v88, v133 offset:34816
	ds_write_b16 v88, v134 offset:35088
	ds_write_b16 v88, v135 offset:35360
	ds_write_b16 v88, v136 offset:35632
	ds_write_b16 v88, v137 offset:36992
	ds_write_b16 v88, v138 offset:37264
	ds_write_b16 v88, v139 offset:37536
	ds_write_b16 v88, v242 offset:37808
	ds_write_b16 v88, v243 offset:39168
	ds_write_b16 v88, v244 offset:39440
	ds_write_b16 v88, v245 offset:39712
	ds_write_b16 v88, v246 offset:39984
	ds_write_b16 v88, v247 offset:41344
	ds_write_b16 v88, v248 offset:41616
	ds_write_b16 v88, v249 offset:41888
	ds_write_b16 v88, v250 offset:42160
	s_waitcnt lgkmcnt(0)
	s_barrier
	ds_read_b128 v[0:3], v91 offset:34816
	ds_read_b128 v[4:7], v91 offset:43520
	ds_read_b128 v[8:11], v91 offset:52224
	ds_read_b128 v[12:15], v91 offset:60928
	v_lshl_add_u64 v[252:253], s[4:5], 0, v[52:53]
	v_lshlrev_b64 v[252:253], 8, v[252:253]
	v_lshl_add_u64 v[252:253], v[54:55], 0, v[252:253]
	s_mov_b64 s[98:99], 0x2000
	v_lshl_add_u64 v[242:243], v[252:253], 0, s[98:99]
	v_lshl_add_u64 v[244:245], v[242:243], 0, s[98:99]
	v_lshl_add_u64 v[246:247], v[244:245], 0, s[98:99]
	s_add_i32 s4, s25, s28
	s_cmpk_gt_i32 s4, 0x3ff
	s_waitcnt lgkmcnt(3)
	global_store_dwordx4 v[252:253], v[0:3], off
	s_waitcnt lgkmcnt(2)
	global_store_dwordx4 v[242:243], v[4:7], off
	s_waitcnt lgkmcnt(1)
	global_store_dwordx4 v[244:245], v[8:11], off
	s_waitcnt lgkmcnt(0)
	global_store_dwordx4 v[246:247], v[12:15], off
	s_cbranch_scc1 .LBB0_235
.LBB0_231:
	s_add_i32 s29, s25, s28
	s_ashr_i32 s4, s29, 7
	s_ashr_i32 s5, s4, 31
	s_lshl_b64 s[14:15], s[4:5], 11
	s_add_i32 s4, s21, s19
	s_and_b32 s4, s4, 0x780
	s_or_b32 s14, s14, s4
	s_and_b32 s98, s29, 7
	s_lshl_b32 s98, s98, 7
	s_and_saveexec_b64 s[16:17], s[0:1]
	s_cbranch_execz .LBB0_233
	s_waitcnt vmcnt(4)
	v_add_f32_e32 v0, v168, v170
	v_add_f32_e32 v2, v172, v174
	v_add_f32_e32 v0, 0, v0
	v_add_f32_e32 v1, v169, v171
	v_add_f32_e32 v4, v176, v178
	v_add_f32_e32 v0, v0, v2
	v_add_f32_e32 v3, v173, v175
	v_add_f32_e32 v6, v180, v182
	v_add_f32_e32 v1, 0, v1
	v_add_f32_e32 v0, v0, v4
	v_add_f32_e32 v5, v177, v179
	v_add_f32_e32 v8, v184, v186
	v_add_f32_e32 v1, v1, v3
	v_add_f32_e32 v0, v0, v6
	v_add_f32_e32 v7, v181, v183
	v_add_f32_e32 v10, v188, v190
	v_add_f32_e32 v1, v1, v5
	v_add_f32_e32 v0, v0, v8
	v_add_f32_e32 v9, v185, v187
	v_add_f32_e32 v12, v192, v194
	v_add_f32_e32 v1, v1, v7
	v_add_f32_e32 v0, v0, v10
	v_add_f32_e32 v11, v189, v191
	v_add_f32_e32 v14, v196, v198
	v_add_f32_e32 v1, v1, v9
	v_add_f32_e32 v0, v0, v12
	v_add_f32_e32 v13, v193, v195
	v_add_f32_e32 v1, v1, v11
	v_add_f32_e32 v0, v0, v14
	v_add_f32_e32 v15, v197, v199
	v_add_f32_e32 v1, v1, v13
	v_mul_f32_e32 v0, 0x3a800000, v0
	v_add_f32_e32 v1, v1, v15
	v_mul_f32_e32 v2, v0, v0
	v_fma_f32 v1, v1, s26, -v2
	v_max_f32_e32 v1, 0, v1
	v_add_f32_e32 v1, 0x3727c5ac, v1
	v_mul_f32_e32 v2, 0x4f800000, v1
	v_cmp_gt_f32_e32 vcc, s27, v1
	s_nop 1
	v_cndmask_b32_e32 v1, v1, v2, vcc
	v_sqrt_f32_e32 v2, v1
	s_nop 0
	v_add_u32_e32 v3, -1, v2
	v_add_u32_e32 v4, 1, v2
	v_fma_f32 v5, -v3, v2, v1
	v_fma_f32 v6, -v4, v2, v1
	v_cmp_ge_f32_e64 s[4:5], 0, v5
	s_nop 1
	v_cndmask_b32_e64 v2, v2, v3, s[4:5]
	v_cmp_lt_f32_e64 s[4:5], 0, v6
	s_nop 1
	v_cndmask_b32_e64 v2, v2, v4, s[4:5]
	v_mul_f32_e32 v3, 0x37800000, v2
	v_cndmask_b32_e32 v2, v2, v3, vcc
	v_cmp_class_f32_e32 vcc, v1, v82
	s_nop 1
	v_cndmask_b32_e32 v1, v2, v1, vcc
	v_div_scale_f32 v2, s[4:5], v1, v1, 1.0
	v_rcp_f32_e32 v3, v2
	v_div_scale_f32 v4, vcc, 1.0, v1, 1.0
	v_fma_f32 v5, -v2, v3, 1.0
	v_fmac_f32_e32 v3, v5, v3
	v_mul_f32_e32 v5, v4, v3
	v_fma_f32 v6, -v2, v5, v4
	v_fmac_f32_e32 v5, v6, v3
	v_fma_f32 v2, -v2, v5, v4
	v_div_fmas_f32 v2, v2, v3, v5
	v_div_fixup_f32 v1, v2, v1, 1.0
	ds_write_b64 v79, v[0:1]
; #define LAS __attribute__((address_space(3)))
; __device__ __forceinline__ unsigned cvt_pk_bf16(float lo, float hi) { unsigned r; asm volatile("v_cvt_pk_bf16_f32 %0, %1, %2" : "=v"(r) : "v"(lo), "v"(hi)); return r; }
; __device__ __forceinline__ float bf_lo(unsigned u) { return __uint_as_float(u << 16); }
; __device__ __forceinline__ float bf_hi(unsigned u) { return __uint_as_float(u & 0xffff0000u); }
; #define LDS_BARRIER() do { asm volatile("s_waitcnt lgkmcnt(0)" ::: "memory"); __builtin_amdgcn_s_barrier(); asm volatile("" ::: "memory"); } while (0)
; __device__ __forceinline__ void sgu_list(LAS unsigned char* lds, const Params& P, int i0, int istride) {
;     ...
; #pragma unroll
;         for (int half = 0; half < 2; ++half) { const int tb = half * 64 + tg * 8;
;             float v0[8], v1[8];
; #pragma unroll
;             for (int j = 0; j < 8; ++j) { const float mean = ST[(tb + j) * 2], rs = ST[(tb + j) * 2 + 1]; const unsigned w = R.vw[half * 8 + j];
;                 v0[j] = (bf_lo(w) - mean) * rs * R.lg0 + R.lb0; v1[j] = (bf_hi(w) - mean) * rs * R.lg1 + R.lb1; }
;             u32x4 o0, o1;
;             o0.x = cvt_pk_bf16(v0[0], v0[1]); o0.y = cvt_pk_bf16(v0[2], v0[3]); o0.z = cvt_pk_bf16(v0[4], v0[5]); o0.w = cvt_pk_bf16(v0[6], v0[7]);
;             o1.x = cvt_pk_bf16(v1[0], v1[1]); o1.y = cvt_pk_bf16(v1[2], v1[3]); o1.z = cvt_pk_bf16(v1[4], v1[5]); o1.w = cvt_pk_bf16(v1[6], v1[7]);
;             *(LAS u32x4*)(VT + c0 * VT_PITCH + tb * 2) = o0; *(LAS u32x4*)(VT + (c0 + 1) * VT_PITCH + tb * 2) = o1; }
; #pragma unroll
;         for (int k = 0; k < 4; ++k) *(LAS u32x4*)(UG + (rr + 32 * k) * VT_PITCH + cc * 2) = R.uu[k];
;         { const int inx = i + istride; if (inx < 1024) sgu_load(R, P, Z, (size_t)(inx >> 7) * SEQ + ((inx >> 3) & 15) * 128, inx & 7, tid); }
;         LDS_BARRIER();
;         bf16x8 Aw[8];
;         { const bf16_t* ap = SguW + ((size_t)gg * 128 + pb * 32 + ml) * 128 + 8 * kh;
; #pragma unroll
;           for (int ks = 0; ks < 8; ++ks) Aw[ks] = *(const bf16x8*)(ap + 16 * ks); }
;         float bsv[16];
; #pragma unroll
;         for (int v = 0; v < 16; ++v) bsv[v] = P.sgu_b[gg * 128 + pb * 32 + (v & 3) + 8 * (v >> 2) + 4 * kh];
.LBB0_233:
	s_or_b64 exec, exec, s[16:17]
	s_waitcnt lgkmcnt(0)
	s_barrier
	ds_read_b128 v[0:3], v89
	ds_read_b128 v[4:7], v89 offset:16
	ds_read_b128 v[8:11], v89 offset:32
	ds_read_b128 v[12:15], v89 offset:48
	s_waitcnt vmcnt(4)
	v_lshlrev_b32_e32 v32, 16, v62
	v_and_b32_e32 v33, 0xffff0000, v62
	s_waitcnt lgkmcnt(3)
	v_sub_f32_e32 v32, v32, v0
	v_sub_f32_e32 v0, v33, v0
	v_mul_f32_e32 v32, v1, v32
	v_mul_f32_e32 v0, v1, v0
	v_and_b32_e32 v1, 0xffff0000, v63
	v_fma_f32 v33, v59, v0, v61
	v_lshlrev_b32_e32 v0, 16, v63
	v_sub_f32_e32 v1, v1, v2
	v_sub_f32_e32 v0, v0, v2
	v_mul_f32_e32 v1, v3, v1
	v_and_b32_e32 v2, 0xffff0000, v64
	v_mul_f32_e32 v0, v3, v0
	v_fma_f32 v34, v59, v1, v61
	v_lshlrev_b32_e32 v1, 16, v64
	s_waitcnt lgkmcnt(2)
	v_sub_f32_e32 v2, v2, v4
	v_and_b32_e32 v3, 0xffff0000, v65
	v_sub_f32_e32 v1, v1, v4
	v_mul_f32_e32 v2, v5, v2
	v_sub_f32_e32 v3, v3, v6
	v_and_b32_e32 v4, 0xffff0000, v66
	v_mul_f32_e32 v1, v5, v1
	v_fma_f32 v5, v59, v2, v61
	v_lshlrev_b32_e32 v2, 16, v65
	v_mul_f32_e32 v3, v7, v3
	s_waitcnt lgkmcnt(1)
	v_sub_f32_e32 v4, v4, v8
	v_sub_f32_e32 v2, v2, v6
	v_fma_f32 v6, v59, v3, v61
	v_lshlrev_b32_e32 v3, 16, v66
	v_mul_f32_e32 v4, v9, v4
	v_mul_f32_e32 v2, v7, v2
	v_sub_f32_e32 v3, v3, v8
	v_fma_f32 v7, v59, v4, v61
	v_lshlrev_b32_e32 v4, 16, v67
	v_and_b32_e32 v8, 0xffff0000, v67
	v_sub_f32_e32 v4, v4, v10
	v_sub_f32_e32 v8, v8, v10
	v_mul_f32_e32 v3, v9, v3
	v_mul_f32_e32 v4, v11, v4
	v_mul_f32_e32 v8, v11, v8
	v_lshlrev_b32_e32 v9, 16, v68
	v_and_b32_e32 v10, 0xffff0000, v68
	v_lshlrev_b32_e32 v11, 16, v69
	s_waitcnt lgkmcnt(0)
	v_sub_f32_e32 v9, v9, v12
	v_sub_f32_e32 v10, v10, v12
	v_sub_f32_e32 v11, v11, v14
	v_and_b32_e32 v12, 0xffff0000, v69
	v_fma_f32 v0, v58, v0, v60
	v_fma_f32 v1, v58, v1, v60
	v_fma_f32 v2, v58, v2, v60
	v_fma_f32 v3, v58, v3, v60
	v_mul_f32_e32 v9, v13, v9
	v_mul_f32_e32 v11, v15, v11
	v_sub_f32_e32 v12, v12, v14
	v_fma_f32 v32, v58, v32, v60
	v_fma_f32 v4, v58, v4, v60
	v_fma_f32 v9, v58, v9, v60
	v_mul_f32_e32 v10, v13, v10
	v_fma_f32 v11, v58, v11, v60
	v_mul_f32_e32 v12, v15, v12
	v_cvt_pk_bf16_f32 v0, v32, v0
	v_cvt_pk_bf16_f32 v1, v1, v2
	v_cvt_pk_bf16_f32 v2, v3, v4
	v_cvt_pk_bf16_f32 v3, v9, v11
	v_fma_f32 v8, v59, v8, v61
	v_fma_f32 v10, v59, v10, v61
	v_fma_f32 v12, v59, v12, v61
	v_cvt_pk_bf16_f32 v4, v33, v34
	v_cvt_pk_bf16_f32 v5, v5, v6
	v_cvt_pk_bf16_f32 v6, v7, v8
	v_cvt_pk_bf16_f32 v7, v10, v12
	ds_write_b128 v83, v[0:3]
	ds_write_b128 v83, v[4:7] offset:272
	ds_read_b64 v[4:5], v90
	v_lshlrev_b32_e32 v0, 16, v70
	v_lshlrev_b32_e32 v10, 16, v71
	v_and_b32_e32 v11, 0xffff0000, v71
	v_and_b32_e32 v33, 0xffff0000, v75
	s_waitcnt lgkmcnt(0)
	v_sub_f32_e32 v0, v0, v4
	v_mul_f32_e32 v0, v5, v0
	v_fma_f32 v8, v58, v0, v60
	v_and_b32_e32 v0, 0xffff0000, v70
	v_sub_f32_e32 v4, v0, v4
	ds_read2_b64 v[0:3], v89 offset0:65 offset1:66
	v_mul_f32_e32 v4, v5, v4
	v_fma_f32 v9, v59, v4, v61
	ds_read2_b64 v[4:7], v89 offset0:67 offset1:68
	s_add_i32 s4, s7, s28
	s_waitcnt lgkmcnt(1)
	v_sub_f32_e32 v10, v10, v0
	v_sub_f32_e32 v0, v11, v0
	v_mul_f32_e32 v0, v1, v0
	v_fma_f32 v11, v59, v0, v61
	v_lshlrev_b32_e32 v0, 16, v72
	v_sub_f32_e32 v0, v0, v2
	v_mul_f32_e32 v0, v3, v0
	v_fma_f32 v12, v58, v0, v60
	v_and_b32_e32 v0, 0xffff0000, v72
	v_sub_f32_e32 v0, v0, v2
	v_mul_f32_e32 v0, v3, v0
	v_fma_f32 v13, v59, v0, v61
	v_lshlrev_b32_e32 v0, 16, v73
	s_waitcnt lgkmcnt(0)
	v_sub_f32_e32 v0, v0, v4
	v_mul_f32_e32 v0, v5, v0
	v_fma_f32 v14, v58, v0, v60
	v_and_b32_e32 v0, 0xffff0000, v73
	v_sub_f32_e32 v0, v0, v4
	v_mul_f32_e32 v0, v5, v0
	v_fma_f32 v15, v59, v0, v61
	v_lshlrev_b32_e32 v0, 16, v74
	v_sub_f32_e32 v0, v0, v6
	v_mul_f32_e32 v0, v7, v0
	v_fma_f32 v32, v58, v0, v60
	v_and_b32_e32 v0, 0xffff0000, v74
	v_mul_f32_e32 v10, v1, v10
	v_sub_f32_e32 v4, v0, v6
	ds_read2_b64 v[0:3], v89 offset0:69 offset1:70
	v_mul_f32_e32 v4, v7, v4
	v_lshlrev_b32_e32 v7, 16, v75
	v_fma_f32 v6, v59, v4, v61
	ds_read_b64 v[4:5], v89 offset:568
	s_waitcnt lgkmcnt(1)
	v_sub_f32_e32 v7, v7, v0
	v_sub_f32_e32 v0, v33, v0
	v_mul_f32_e32 v0, v1, v0
	v_fma_f32 v33, v59, v0, v61
	v_lshlrev_b32_e32 v0, 16, v76
	v_sub_f32_e32 v0, v0, v2
	v_mul_f32_e32 v0, v3, v0
	v_fma_f32 v34, v58, v0, v60
	v_and_b32_e32 v0, 0xffff0000, v76
	v_sub_f32_e32 v0, v0, v2
	v_mul_f32_e32 v0, v3, v0
	v_fma_f32 v35, v59, v0, v61
	v_lshlrev_b32_e32 v0, 16, v77
	s_waitcnt lgkmcnt(0)
	v_sub_f32_e32 v0, v0, v4
	v_mul_f32_e32 v0, v5, v0
	v_fma_f32 v3, v58, v0, v60
	v_and_b32_e32 v0, 0xffff0000, v77
	v_sub_f32_e32 v0, v0, v4
	v_mul_f32_e32 v7, v1, v7
	v_mul_f32_e32 v0, v5, v0
	v_fma_f32 v10, v58, v10, v60
	v_fma_f32 v7, v58, v7, v60
	v_fma_f32 v36, v59, v0, v61
	v_cvt_pk_bf16_f32 v0, v8, v10
	v_cvt_pk_bf16_f32 v1, v12, v14
	v_cvt_pk_bf16_f32 v2, v32, v7
	v_cvt_pk_bf16_f32 v3, v34, v3
	s_cmpk_gt_i32 s4, 0x3ff
	v_cvt_pk_bf16_f32 v4, v9, v11
	v_cvt_pk_bf16_f32 v5, v13, v15
	v_cvt_pk_bf16_f32 v6, v6, v33
	v_cvt_pk_bf16_f32 v7, v35, v36
	ds_write_b128 v84, v[0:3]
	ds_write_b128 v84, v[4:7] offset:272
	ds_write_b128 v91, v[16:19] offset:34816
	ds_write_b128 v91, v[20:23] offset:43520
	ds_write_b128 v91, v[24:27] offset:52224
	ds_write_b128 v91, v[28:31] offset:60928
	v_or_b32_e32 v218, s98, v81
	v_lshlrev_b32_e32 v218, 8, v218
	v_mov_b32_e32 v219, 0
	v_lshl_add_u64 v[218:219], v[56:57], 0, v[218:219]
	global_load_dwordx4 v[92:95], v[218:219], off
	global_load_dwordx4 v[96:99], v[218:219], off offset:32
	global_load_dwordx4 v[100:103], v[218:219], off offset:64
	global_load_dwordx4 v[104:107], v[218:219], off offset:96
	global_load_dwordx4 v[108:111], v[218:219], off offset:128
	global_load_dwordx4 v[112:115], v[218:219], off offset:160
	global_load_dwordx4 v[116:119], v[218:219], off offset:192
	global_load_dwordx4 v[120:123], v[218:219], off offset:224
	v_or_b32_e32 v220, s98, v80
	v_lshlrev_b32_e32 v220, 2, v220
	global_load_dwordx4 v[140:143], v220, s[12:13]
	global_load_dwordx4 v[144:147], v220, s[12:13] offset:32
	global_load_dwordx4 v[148:151], v220, s[12:13] offset:64
	global_load_dwordx4 v[152:155], v220, s[12:13] offset:96
	s_cbranch_scc1 .Lsgu_last
; __device__ __forceinline__ void sgu_list(LAS unsigned char* lds, const Params& P, int i0, int istride) {
;     ...
;         const int gg = i & 7; const size_t R0 = (size_t)(i >> 7) * SEQ + ((i >> 3) & 15) * 128;
;         if (tid < 128) { const f32x4* sp = (const f32x4*)((const float*)(P.ws + WS_STATS) + (R0 + tid) * 32); float s1 = 0.f, ss = 0.f;
; #pragma unroll
;             for (int k = 0; k < 8; ++k) { const f32x4 v = sp[k]; s1 += v[0] + v[2]; ss += v[1] + v[3]; }
;             const float mean = s1 * (1.0f / 1024.0f), var = fmaxf(ss * (1.0f / 1024.0f) - mean * mean, 0.f);
;             ST[tid * 2] = mean; ST[tid * 2 + 1] = 1.0f / sqrtf(var + 1e-5f); }
;     ...
;         { const int inx = i + istride; if (inx < 1024) sgu_load(R, P, Z, (size_t)(inx >> 7) * SEQ + ((inx >> 3) & 15) * 128, inx & 7, tid); }
	s_ashr_i32 s16, s4, 7
	s_ashr_i32 s17, s16, 31
	s_add_i32 s5, s18, s19
	s_and_b32 s30, s4, 7
	s_lshl_b64 s[16:17], s[16:17], 11
	s_and_b32 s5, s5, 0x780
	s_lshl_b32 s31, s30, 14
	s_or_b32 s16, s16, s5
	s_or_b32 s4, s31, 0x60000
	s_add_u32 s4, s16, s4
	s_addc_u32 s5, s17, 0
	v_lshl_add_u64 v[0:1], s[4:5], 0, v[46:47]
	v_lshlrev_b64 v[0:1], 8, v[0:1]
	v_lshl_add_u64 v[0:1], v[50:51], 0, v[0:1]
	s_bitset1_b32 s31, 18
	global_load_dword v62, v[0:1], off
	global_load_dword v63, v[0:1], off offset:256
	global_load_dword v64, v[0:1], off offset:512
	global_load_dword v65, v[0:1], off offset:768
	global_load_dword v66, v[0:1], off offset:1024
	global_load_dword v67, v[0:1], off offset:1280
	global_load_dword v68, v[0:1], off offset:1536
	global_load_dword v69, v[0:1], off offset:1792
	v_add_co_u32_e32 v0, vcc, s6, v0
	s_add_u32 s4, s31, s16
	s_nop 0
	v_addc_co_u32_e32 v1, vcc, 0, v1, vcc
	s_addc_u32 s5, s17, 0
	global_load_dword v70, v[0:1], off
	global_load_dword v71, v[0:1], off offset:256
	global_load_dword v72, v[0:1], off offset:512
	global_load_dword v73, v[0:1], off offset:768
	global_load_dword v74, v[0:1], off offset:1024
	global_load_dword v75, v[0:1], off offset:1280
	global_load_dword v76, v[0:1], off offset:1536
	global_load_dword v77, v[0:1], off offset:1792
	v_lshl_add_u64 v[0:1], s[4:5], 0, v[52:53]
	v_lshlrev_b64 v[0:1], 8, v[0:1]
	v_lshl_add_u64 v[0:1], v[54:55], 0, v[0:1]
	v_add_co_u32_e32 v2, vcc, 0x2000, v0
	s_nop 1
	v_addc_co_u32_e32 v3, vcc, 0, v1, vcc
	global_load_dwordx4 v[16:19], v[0:1], off
	global_load_dwordx4 v[20:23], v[2:3], off
	v_add_co_u32_e32 v2, vcc, 0x4000, v0
	s_nop 1
	v_addc_co_u32_e32 v3, vcc, 0, v1, vcc
	v_add_co_u32_e32 v0, vcc, 0x6000, v0
	s_nop 1
	v_addc_co_u32_e32 v1, vcc, 0, v1, vcc
	global_load_dwordx4 v[24:27], v[2:3], off
	global_load_dwordx4 v[28:31], v[0:1], off
	v_lshl_or_b32 v0, s30, 9, v78
	global_load_dwordx2 v[58:59], v0, s[66:67]
	global_load_dwordx2 v[60:61], v0, s[8:9]
	v_lshl_add_u64 v[218:219], s[16:17], 0, v[216:217]
	v_lshlrev_b64 v[218:219], 7, v[218:219]
	v_lshl_add_u64 v[218:219], s[10:11], 0, v[218:219]
	global_load_dwordx4 v[168:171], v[218:219], off
	global_load_dwordx4 v[172:175], v[218:219], off offset:16
	global_load_dwordx4 v[176:179], v[218:219], off offset:32
	global_load_dwordx4 v[180:183], v[218:219], off offset:48
	global_load_dwordx4 v[184:187], v[218:219], off offset:64
	global_load_dwordx4 v[188:191], v[218:219], off offset:80
	global_load_dwordx4 v[192:195], v[218:219], off offset:96
	global_load_dwordx4 v[196:199], v[218:219], off offset:112
	s_branch .LBB0_230
.Lsgu_last:
	s_waitcnt vmcnt(0)
	s_branch .LBB0_230

; __global__ void __launch_bounds__(NTHREADS, 2) fwd_megakernel(Params P) {
	.amdhsa_kernel _Z14fwd_megakernel6Params
		.amdhsa_group_segment_fixed_size 0
		.amdhsa_private_segment_fixed_size 0
		.amdhsa_kernarg_size 472
		.amdhsa_user_sgpr_count 2
		.amdhsa_user_sgpr_dispatch_ptr 0
		.amdhsa_user_sgpr_queue_ptr 0
		.amdhsa_user_sgpr_kernarg_segment_ptr 1
		.amdhsa_user_sgpr_dispatch_id 0
		.amdhsa_user_sgpr_kernarg_preload_length 0
		.amdhsa_user_sgpr_kernarg_preload_offset 0
		.amdhsa_user_sgpr_private_segment_size 0
		.amdhsa_uses_dynamic_stack 0
		.amdhsa_enable_private_segment 0
		.amdhsa_system_sgpr_workgroup_id_x 1
		.amdhsa_system_sgpr_workgroup_id_y 0
		.amdhsa_system_sgpr_workgroup_id_z 0
		.amdhsa_system_sgpr_workgroup_info 0
		.amdhsa_system_vgpr_workitem_id 2
		.amdhsa_next_free_vgpr 256
		.amdhsa_next_free_sgpr 102
		.amdhsa_accum_offset 256
		.amdhsa_reserve_vcc 1
		.amdhsa_float_round_mode_32 0
		.amdhsa_float_round_mode_16_64 0
		.amdhsa_float_denorm_mode_32 3
		.amdhsa_float_denorm_mode_16_64 3
		.amdhsa_dx10_clamp 1
		.amdhsa_ieee_mode 1
		.amdhsa_fp16_overflow 0
		.amdhsa_tg_split 0
		.amdhsa_exception_fp_ieee_invalid_op 0
		.amdhsa_exception_fp_denorm_src 0
		.amdhsa_exception_fp_ieee_div_zero 0
		.amdhsa_exception_fp_ieee_overflow 0
		.amdhsa_exception_fp_ieee_underflow 0
		.amdhsa_exception_fp_ieee_inexact 0
		.amdhsa_exception_int_div_zero 0
	.end_amdhsa_kernel

; __global__ void __launch_bounds__(NTHREADS, 2) fwd_megakernel(Params P) {
amdhsa.kernels:
  - .agpr_count:     0
    .args:
      - .offset:         0
        .size:           216
        .value_kind:     by_value
      - .offset:         216
        .size:           4
        .value_kind:     hidden_block_count_x
      - .offset:         220
        .size:           4
        .value_kind:     hidden_block_count_y
      - .offset:         224
        .size:           4
        .value_kind:     hidden_block_count_z
      - .offset:         228
        .size:           2
        .value_kind:     hidden_group_size_x
      - .offset:         230
        .size:           2
        .value_kind:     hidden_group_size_y
      - .offset:         232
        .size:           2
        .value_kind:     hidden_group_size_z
      - .offset:         234
        .size:           2
        .value_kind:     hidden_remainder_x
      - .offset:         236
        .size:           2
        .value_kind:     hidden_remainder_y
      - .offset:         238
        .size:           2
        .value_kind:     hidden_remainder_z
      - .offset:         256
        .size:           8
        .value_kind:     hidden_global_offset_x
      - .offset:         264
        .size:           8
        .value_kind:     hidden_global_offset_y
      - .offset:         272
        .size:           8
        .value_kind:     hidden_global_offset_z
      - .offset:         280
        .size:           2
        .value_kind:     hidden_grid_dims
      - .offset:         304
        .size:           8
        .value_kind:     hidden_multigrid_sync_arg
      - .offset:         336
        .size:           4
        .value_kind:     hidden_dynamic_lds_size
    .group_segment_fixed_size: 0
    .kernarg_segment_align: 8
    .kernarg_segment_size: 472
    .language:       OpenCL C
    .language_version:
      - 2
      - 0
    .max_flat_workgroup_size: 512
    .name:           _Z14fwd_megakernel6Params
    .private_segment_fixed_size: 0
    .sgpr_count:     108
    .sgpr_spill_count: 26
    .symbol:         _Z14fwd_megakernel6Params.kd
    .uniform_work_group_size: 1
    .uses_dynamic_stack: false
    .vgpr_count:     256
    .vgpr_spill_count: 0
    .wavefront_size: 64
